# v79 plus write-through (sc1) stores for the FFN-up H outputs and the FFN-up0 idle-round prep outputs
# baseline (speedup 1.0000x reference)
; #define LAS __attribute__((address_space(3)))
; __host__ __device__ __forceinline__ int gate_row(int n) { if (n < 512) return n; const int base = n < 1536 ? 512 : 1536, q = n - base, h = q >> 9, t = (q & 511) >> 7, r = q & 127; return base + t * 256 + h * 128 + r; }
; template <bool GATEMAP = false>
; __device__ __forceinline__ void p0_transpose_item(const float* W, int N, bf16* WT, int ldwt, int koff, const float* gain, LAS float* scr, int item, int lane) {
;     const int nblk = N / 64, kb = item / nblk, nb = item % nblk, k0 = 64 * kb, n0 = 64 * nb; const int nd0 = GATEMAP ? gate_row(n0) : n0;
;     const int ks = lane >> 4, n4 = (lane & 15) * 4;
;     f32x4 v[16];
; #pragma unroll
;     for (int i = 0; i < 16; ++i) v[i] = *(const f32x4*)(W + (size_t)(k0 + 4 * i + ks) * N + n0 + n4);
;     if (gain) {
; #pragma unroll
;         for (int i = 0; i < 16; ++i) v[i] = v[i] * gain[k0 + 4 * i + ks];
;     }
; #pragma unroll
;     for (int i = 0; i < 16; ++i) { LAS float* d = scr + (4 * i + ks) * 65 + n4; d[0] = v[i][0]; d[1] = v[i][1]; d[2] = v[i][2]; d[3] = v[i][3]; }
.LBB0_508:
	s_ashr_i32 s0, s13, 31
	s_lshr_b32 s0, s0, 28
	s_add_i32 s0, s13, s0
	s_ashr_i32 s0, s0, 4
	s_lshl_b32 s2, s0, 6
	s_lshl_b32 s0, s0, 10
	v_or_b32_e32 v46, s2, v8
	s_sub_i32 s0, s4, s0
	v_or_b32_e32 v48, 4, v46
	v_or_b32_e32 v50, 8, v46
	v_or_b32_e32 v52, 12, v46
	v_or_b32_e32 v54, 16, v46
	v_or_b32_e32 v56, 20, v46
	v_or_b32_e32 v58, 24, v46
	v_or_b32_e32 v60, 28, v46
	v_or_b32_e32 v62, 32, v46
	v_or_b32_e32 v64, 36, v46
	v_or_b32_e32 v66, 40, v46
	v_or_b32_e32 v68, 44, v46
	v_or_b32_e32 v70, 48, v46
	v_or_b32_e32 v72, 52, v46
	v_or_b32_e32 v74, 56, v46
	v_or_b32_e32 v76, 60, v46
	s_ashr_i32 s1, s0, 31
	v_ashrrev_i32_e32 v47, 31, v46
	v_ashrrev_i32_e32 v49, 31, v48
	v_ashrrev_i32_e32 v51, 31, v50
	v_ashrrev_i32_e32 v53, 31, v52
	v_ashrrev_i32_e32 v55, 31, v54
	v_ashrrev_i32_e32 v57, 31, v56
	v_ashrrev_i32_e32 v59, 31, v58
	v_ashrrev_i32_e32 v61, 31, v60
	v_ashrrev_i32_e32 v63, 31, v62
	v_ashrrev_i32_e32 v65, 31, v64
	v_ashrrev_i32_e32 v67, 31, v66
	v_ashrrev_i32_e32 v69, 31, v68
	v_ashrrev_i32_e32 v71, 31, v70
	v_ashrrev_i32_e32 v73, 31, v72
	v_ashrrev_i32_e32 v75, 31, v74
	v_ashrrev_i32_e32 v77, 31, v76
	v_lshl_add_u64 v[78:79], s[0:1], 2, v[2:3]
	v_lshlrev_b64 v[46:47], 12, v[46:47]
	v_lshlrev_b64 v[80:81], 12, v[48:49]
	v_lshlrev_b64 v[50:51], 12, v[50:51]
	v_lshlrev_b64 v[52:53], 12, v[52:53]
	v_lshlrev_b64 v[54:55], 12, v[54:55]
	v_lshlrev_b64 v[56:57], 12, v[56:57]
	v_lshlrev_b64 v[58:59], 12, v[58:59]
	v_lshlrev_b64 v[60:61], 12, v[60:61]
	v_lshlrev_b64 v[62:63], 12, v[62:63]
	v_lshlrev_b64 v[64:65], 12, v[64:65]
	v_lshlrev_b64 v[66:67], 12, v[66:67]
	v_lshlrev_b64 v[68:69], 12, v[68:69]
	v_lshlrev_b64 v[70:71], 12, v[70:71]
	v_lshlrev_b64 v[72:73], 12, v[72:73]
	v_lshlrev_b64 v[74:75], 12, v[74:75]
	v_lshlrev_b64 v[76:77], 12, v[76:77]
	v_lshl_add_u64 v[46:47], v[78:79], 0, v[46:47]
	v_lshl_add_u64 v[80:81], v[78:79], 0, v[80:81]
	v_lshl_add_u64 v[82:83], v[78:79], 0, v[50:51]
	v_lshl_add_u64 v[84:85], v[78:79], 0, v[52:53]
	v_lshl_add_u64 v[86:87], v[78:79], 0, v[54:55]
	v_lshl_add_u64 v[88:89], v[78:79], 0, v[56:57]
	v_lshl_add_u64 v[90:91], v[78:79], 0, v[58:59]
	v_lshl_add_u64 v[92:93], v[78:79], 0, v[60:61]
	v_lshl_add_u64 v[94:95], v[78:79], 0, v[62:63]
	v_lshl_add_u64 v[96:97], v[78:79], 0, v[64:65]
	v_lshl_add_u64 v[98:99], v[78:79], 0, v[66:67]
	v_lshl_add_u64 v[100:101], v[78:79], 0, v[68:69]
	v_lshl_add_u64 v[102:103], v[78:79], 0, v[70:71]
	v_lshl_add_u64 v[104:105], v[78:79], 0, v[72:73]
	v_lshl_add_u64 v[106:107], v[78:79], 0, v[74:75]
	v_lshl_add_u64 v[108:109], v[78:79], 0, v[76:77]
	global_load_dwordx4 v[46:49], v[46:47], off
	s_nop 0
	global_load_dwordx4 v[50:53], v[80:81], off
	global_load_dwordx4 v[54:57], v[82:83], off
	global_load_dwordx4 v[58:61], v[84:85], off
	global_load_dwordx4 v[62:65], v[86:87], off
	global_load_dwordx4 v[66:69], v[88:89], off
	global_load_dwordx4 v[70:73], v[90:91], off
	global_load_dwordx4 v[74:77], v[92:93], off
	global_load_dwordx4 v[78:81], v[94:95], off
	global_load_dwordx4 v[82:85], v[96:97], off
	s_nop 0
	global_load_dwordx4 v[86:89], v[98:99], off
	global_load_dwordx4 v[90:93], v[100:101], off
	global_load_dwordx4 v[94:97], v[102:103], off
	s_nop 0
	global_load_dwordx4 v[98:101], v[104:105], off
	s_nop 0
	global_load_dwordx4 v[102:105], v[106:107], off
	s_nop 0
	global_load_dwordx4 v[106:109], v[108:109], off
	v_add_u32_e32 v6, s0, v9
	s_ashr_i32 s3, s2, 31
	v_ashrrev_i32_e32 v7, 31, v6
	v_lshl_add_u64 v[4:5], s[2:3], 1, v[0:1]
	v_lshlrev_b64 v[122:123], 13, v[6:7]
	v_add_u32_e32 v110, 8, v6
	v_lshl_add_u64 v[122:123], v[4:5], 0, v[122:123]
	v_ashrrev_i32_e32 v111, 31, v110
	v_lshlrev_b64 v[110:111], 13, v[110:111]
	v_add_u32_e32 v112, 16, v6
	v_lshl_add_u64 v[110:111], v[4:5], 0, v[110:111]
	v_ashrrev_i32_e32 v113, 31, v112
	v_lshlrev_b64 v[112:113], 13, v[112:113]
	v_add_u32_e32 v114, 24, v6
	v_lshl_add_u64 v[112:113], v[4:5], 0, v[112:113]
	s_waitcnt vmcnt(15)
	ds_write2_b32 v11, v46, v47 offset1:1
	ds_write2_b32 v11, v48, v49 offset0:2 offset1:3
	s_waitcnt vmcnt(14)
	ds_write2_b32 v12, v50, v51 offset1:1
	ds_write2_b32 v13, v52, v53 offset1:1
	s_waitcnt vmcnt(13)
	ds_write2_b32 v14, v54, v55 offset1:1
	ds_write2_b32 v15, v56, v57 offset1:1
	s_waitcnt vmcnt(12)
	ds_write2_b32 v16, v58, v59 offset1:1
	ds_write2_b32 v17, v60, v61 offset1:1
	s_waitcnt vmcnt(11)
	ds_write2_b32 v18, v62, v63 offset1:1
	ds_write2_b32 v19, v64, v65 offset1:1
	s_waitcnt vmcnt(10)
	ds_write2_b32 v20, v66, v67 offset1:1
	ds_write2_b32 v21, v68, v69 offset1:1
	s_waitcnt vmcnt(9)
	ds_write2_b32 v22, v70, v71 offset1:1
	ds_write2_b32 v23, v72, v73 offset1:1
	s_waitcnt vmcnt(8)
	ds_write2_b32 v24, v74, v75 offset1:1
	ds_write2_b32 v25, v76, v77 offset1:1
	s_waitcnt vmcnt(7)
	ds_write2_b32 v26, v78, v79 offset1:1
	ds_write2_b32 v27, v80, v81 offset1:1
	s_waitcnt vmcnt(6)
	ds_write2_b32 v28, v82, v83 offset1:1
	ds_write2_b32 v29, v84, v85 offset1:1
	s_waitcnt vmcnt(5)
	ds_write2_b32 v30, v86, v87 offset1:1
	ds_write2_b32 v31, v88, v89 offset1:1
	s_waitcnt vmcnt(4)
	ds_write2_b32 v32, v90, v91 offset1:1
	ds_write2_b32 v33, v92, v93 offset1:1
	s_waitcnt vmcnt(3)
; #define LAS __attribute__((address_space(3)))
; __device__ __forceinline__ unsigned pk2(float lo, float hi) { return pg8::cvt_pk_bf16(lo, hi); }
; template <bool GATEMAP = false>
; __device__ __forceinline__ void p0_transpose_item(const float* W, int N, bf16* WT, int ldwt, int koff, const float* gain, LAS float* scr, int item, int lane) {
;     ...
;     const int c = lane & 7;
; #pragma unroll
;     for (int j = 0; j < 8; ++j) { const int n = (lane >> 3) + 8 * j; const LAS float* q = scr + (8 * c) * 65 + n;
;         v4u o; o.x = pk2(q[0 * 65], q[1 * 65]); o.y = pk2(q[2 * 65], q[3 * 65]); o.z = pk2(q[4 * 65], q[5 * 65]); o.w = pk2(q[6 * 65], q[7 * 65]);
;         *(v4u*)(WT + (size_t)(nd0 + n) * ldwt + koff + k0 + 8 * c) = o; }
;     asm volatile("s_waitcnt lgkmcnt(0)" ::: "memory");
	ds_write2_b32 v34, v94, v95 offset1:1
	ds_write2_b32 v35, v96, v97 offset1:1
	s_waitcnt vmcnt(2)
	ds_write2_b32 v36, v98, v99 offset1:1
	ds_write2_b32 v37, v100, v101 offset1:1
	s_waitcnt vmcnt(1)
	ds_write2_b32 v38, v102, v103 offset1:1
	ds_write2_b32 v39, v104, v105 offset1:1
	s_waitcnt vmcnt(0)
	ds_write2_b32 v42, v106, v107 offset1:1
	ds_write2_b32 v43, v108, v109 offset1:1
	s_waitcnt lgkmcnt(0)
	ds_read2_b32 v[46:47], v10 offset1:65
	s_waitcnt lgkmcnt(0)
	v_cvt_pk_bf16_f32 v46, v46, v47
	ds_read2_b32 v[48:49], v10 offset0:130 offset1:195
	s_waitcnt lgkmcnt(0)
	v_cvt_pk_bf16_f32 v47, v48, v49
	ds_read2_b32 v[48:49], v44 offset0:4 offset1:69
	s_waitcnt lgkmcnt(0)
	v_cvt_pk_bf16_f32 v48, v48, v49
	ds_read2_b32 v[50:51], v44 offset0:134 offset1:199
	s_waitcnt lgkmcnt(0)
	v_cvt_pk_bf16_f32 v49, v50, v51
	ds_read2_b32 v[50:51], v10 offset0:8 offset1:73
	global_store_dwordx4 v[122:123], v[46:49], off sc1
	v_ashrrev_i32_e32 v115, 31, v114
	v_lshlrev_b64 v[114:115], 13, v[114:115]
	s_waitcnt lgkmcnt(0)
	v_cvt_pk_bf16_f32 v46, v50, v51
	ds_read2_b32 v[48:49], v10 offset0:138 offset1:203
	s_waitcnt lgkmcnt(0)
	v_cvt_pk_bf16_f32 v47, v48, v49
	ds_read2_b32 v[48:49], v44 offset0:12 offset1:77
	s_waitcnt lgkmcnt(0)
	v_cvt_pk_bf16_f32 v48, v48, v49
	ds_read2_b32 v[50:51], v44 offset0:142 offset1:207
	s_waitcnt lgkmcnt(0)
	v_cvt_pk_bf16_f32 v49, v50, v51
	ds_read2_b32 v[50:51], v10 offset0:16 offset1:81
	global_store_dwordx4 v[110:111], v[46:49], off sc1
	v_add_u32_e32 v116, 32, v6
	v_lshl_add_u64 v[114:115], v[4:5], 0, v[114:115]
	s_waitcnt lgkmcnt(0)
	v_cvt_pk_bf16_f32 v46, v50, v51
	ds_read2_b32 v[48:49], v10 offset0:146 offset1:211
	s_waitcnt lgkmcnt(0)
	v_cvt_pk_bf16_f32 v47, v48, v49
	ds_read2_b32 v[48:49], v44 offset0:20 offset1:85
	s_waitcnt lgkmcnt(0)
	v_cvt_pk_bf16_f32 v48, v48, v49
	ds_read2_b32 v[50:51], v44 offset0:150 offset1:215
	s_waitcnt lgkmcnt(0)
	v_cvt_pk_bf16_f32 v49, v50, v51
	ds_read2_b32 v[50:51], v10 offset0:24 offset1:89
	global_store_dwordx4 v[112:113], v[46:49], off sc1
	v_ashrrev_i32_e32 v117, 31, v116
	v_lshlrev_b64 v[116:117], 13, v[116:117]
	s_waitcnt lgkmcnt(0)
	v_cvt_pk_bf16_f32 v46, v50, v51
	ds_read2_b32 v[48:49], v10 offset0:154 offset1:219
	s_waitcnt lgkmcnt(0)
	v_cvt_pk_bf16_f32 v47, v48, v49
	ds_read2_b32 v[48:49], v44 offset0:28 offset1:93
	s_waitcnt lgkmcnt(0)
	v_cvt_pk_bf16_f32 v48, v48, v49
	ds_read2_b32 v[50:51], v44 offset0:158 offset1:223
	s_waitcnt lgkmcnt(0)
	v_cvt_pk_bf16_f32 v49, v50, v51
	ds_read2_b32 v[50:51], v10 offset0:32 offset1:97
	global_store_dwordx4 v[114:115], v[46:49], off sc1
	v_add_u32_e32 v118, 40, v6
	v_lshl_add_u64 v[116:117], v[4:5], 0, v[116:117]
	s_waitcnt lgkmcnt(0)
	v_cvt_pk_bf16_f32 v46, v50, v51
	ds_read2_b32 v[48:49], v10 offset0:162 offset1:227
	s_waitcnt lgkmcnt(0)
	v_cvt_pk_bf16_f32 v47, v48, v49
	ds_read2_b32 v[48:49], v44 offset0:36 offset1:101
	s_waitcnt lgkmcnt(0)
	v_cvt_pk_bf16_f32 v48, v48, v49
	ds_read2_b32 v[50:51], v44 offset0:166 offset1:231
	s_waitcnt lgkmcnt(0)
	v_cvt_pk_bf16_f32 v49, v50, v51
	v_ashrrev_i32_e32 v119, 31, v118
	ds_read2_b32 v[50:51], v10 offset0:40 offset1:105
	global_store_dwordx4 v[116:117], v[46:49], off sc1
	v_lshlrev_b64 v[118:119], 13, v[118:119]
	v_add_u32_e32 v120, 48, v6
	s_waitcnt lgkmcnt(0)
	v_cvt_pk_bf16_f32 v46, v50, v51
	ds_read2_b32 v[48:49], v10 offset0:170 offset1:235
	s_waitcnt lgkmcnt(0)
	v_cvt_pk_bf16_f32 v47, v48, v49
	ds_read2_b32 v[48:49], v44 offset0:44 offset1:109
	v_lshl_add_u64 v[118:119], v[4:5], 0, v[118:119]
	s_waitcnt lgkmcnt(0)
	v_cvt_pk_bf16_f32 v48, v48, v49
	ds_read2_b32 v[50:51], v44 offset0:174 offset1:239
	s_waitcnt lgkmcnt(0)
	v_cvt_pk_bf16_f32 v49, v50, v51
	v_ashrrev_i32_e32 v121, 31, v120
	ds_read2_b32 v[50:51], v10 offset0:48 offset1:113
	global_store_dwordx4 v[118:119], v[46:49], off sc1
	v_lshlrev_b64 v[120:121], 13, v[120:121]
	v_add_u32_e32 v6, 56, v6
	s_waitcnt lgkmcnt(0)
	v_cvt_pk_bf16_f32 v46, v50, v51
	ds_read2_b32 v[48:49], v10 offset0:178 offset1:243
	s_waitcnt lgkmcnt(0)
	v_cvt_pk_bf16_f32 v47, v48, v49
	ds_read2_b32 v[48:49], v44 offset0:52 offset1:117
	v_lshl_add_u64 v[120:121], v[4:5], 0, v[120:121]
	s_waitcnt lgkmcnt(0)
	v_cvt_pk_bf16_f32 v48, v48, v49
	ds_read2_b32 v[50:51], v44 offset0:182 offset1:247
	s_waitcnt lgkmcnt(0)
	v_cvt_pk_bf16_f32 v49, v50, v51
	v_ashrrev_i32_e32 v7, 31, v6
	ds_read2_b32 v[50:51], v10 offset0:56 offset1:121
	global_store_dwordx4 v[120:121], v[46:49], off sc1
	v_lshlrev_b64 v[6:7], 13, v[6:7]
	v_lshl_add_u64 v[4:5], v[4:5], 0, v[6:7]
	s_waitcnt lgkmcnt(0)
	v_cvt_pk_bf16_f32 v46, v50, v51
	ds_read2_b32 v[48:49], v10 offset0:186 offset1:251
	s_waitcnt lgkmcnt(0)
	v_cvt_pk_bf16_f32 v47, v48, v49
	ds_read2_b32 v[48:49], v44 offset0:60 offset1:125
	s_waitcnt lgkmcnt(0)
	v_cvt_pk_bf16_f32 v48, v48, v49
	ds_read2_b32 v[50:51], v44 offset0:190 offset1:255
	s_waitcnt lgkmcnt(0)
	v_cvt_pk_bf16_f32 v49, v50, v51
	global_store_dwordx4 v[4:5], v[46:49], off sc1
	s_waitcnt lgkmcnt(0)
	s_add_i32 s13, s13, s12
	s_add_i32 s4, s4, s5
	s_cmpk_gt_i32 s13, 0x3ff
	s_cbranch_scc0 .LBB0_508
	s_cmpk_lg_i32 s7, 0xc0
	s_cbranch_scc1 .Lprep2_skipw2
	s_branch .LBB0_513

; template <int PART>
; __device__ __forceinline__ void phase_prologue_late(const Params& p, LAS unsigned char* lds, int cu0) {
;     ...
;             for (int d0 = 0; d0 < 128; d0 += 16) {
;                 float wv[16];
; #pragma unroll
;                 for (int dd = 0; dd < 16; ++dd) wv[dd] = Wo[(size_t)(g * 128 + d0 + dd) * D + n];
; #pragma unroll
;                 for (int dd = 0; dd < 16; ++dd) { const float w = wv[dd] * sc[g * 128 + d0 + dd];
; #pragma unroll
;                     for (int i = 0; i < 8; ++i) acc[i] += wp[i * 128 + d0 + dd] * w; }
.LBB0_511:
	v_add_u32_e32 v196, s38, v177
	v_add_co_u32_e32 v0, vcc, 0xffff1000, v26
	s_add_u32 s24, s18, s38
	s_nop 0
	v_addc_co_u32_e32 v1, vcc, -1, v27, vcc
	v_add_co_u32_e32 v16, vcc, 0xffff2000, v26
	s_addc_u32 s25, s19, s39
	s_nop 0
	v_addc_co_u32_e32 v17, vcc, -1, v27, vcc
	v_add_co_u32_e32 v18, vcc, 0xffff3000, v26
	s_add_u32 s42, s4, s38
	s_nop 0
	v_addc_co_u32_e32 v19, vcc, -1, v27, vcc
	v_add_co_u32_e32 v38, vcc, 0xffff4000, v26
	s_addc_u32 s43, s17, s39
	s_nop 0
	v_addc_co_u32_e32 v39, vcc, -1, v27, vcc
	v_add_co_u32_e32 v162, vcc, 0xffff5000, v26
	global_load_dword v36, v[26:27], off offset:-4096
	global_load_dword v37, v[26:27], off
	v_addc_co_u32_e32 v163, vcc, -1, v27, vcc
	global_load_dword v24, v[0:1], off
	s_nop 0
	global_load_dwordx4 v[0:3], v25, s[24:25] offset:48
	global_load_dwordx4 v[4:7], v25, s[24:25] offset:32
	global_load_dwordx4 v[12:15], v25, s[24:25]
	global_load_dwordx4 v[8:11], v25, s[24:25] offset:16
	global_load_dword v172, v[16:17], off
	global_load_dword v173, v[18:19], off
	ds_read_b128 v[42:45], v196 offset:48
	ds_read_b128 v[46:49], v196 offset:32
	ds_read_b128 v[50:53], v196 offset:16
	ds_read_b128 v[54:57], v196
	s_nop 0
	ds_read_b128 v[16:19], v196 offset:560
	ds_read_b128 v[58:61], v196 offset:544
	ds_read_b128 v[62:65], v196 offset:528
	ds_read_b128 v[66:69], v196 offset:512
	ds_read_b128 v[70:73], v196 offset:1072
	ds_read_b128 v[74:77], v196 offset:1056
	ds_read_b128 v[78:81], v196 offset:1040
	ds_read_b128 v[82:85], v196 offset:1024
	ds_read_b128 v[20:23], v196 offset:1584
	ds_read_b128 v[86:89], v196 offset:1568
	ds_read_b128 v[90:93], v196 offset:1552
	ds_read_b128 v[94:97], v196 offset:1536
	ds_read_b128 v[98:101], v196 offset:2096
	ds_read_b128 v[102:105], v196 offset:2080
	ds_read_b128 v[106:109], v196 offset:2064
	ds_read_b128 v[110:113], v196 offset:2048
	ds_read_b128 v[114:117], v196 offset:2608
	ds_read_b128 v[118:121], v196 offset:2592
	ds_read_b128 v[122:125], v196 offset:2576
	ds_read_b128 v[126:129], v196 offset:2560
	ds_read_b128 v[130:133], v196 offset:3120
	ds_read_b128 v[134:137], v196 offset:3104
	ds_read_b128 v[138:141], v196 offset:3088
	ds_read_b128 v[142:145], v196 offset:3072
	ds_read_b128 v[146:149], v196 offset:3632
	ds_read_b128 v[150:153], v196 offset:3616
	ds_read_b128 v[154:157], v196 offset:3600
	ds_read_b128 v[158:161], v196 offset:3584
	global_load_dword v176, v[38:39], off
	v_add_co_u32_e32 v38, vcc, 0xffff6000, v26
	s_add_i32 s20, s20, 16
	s_nop 0
	v_addc_co_u32_e32 v39, vcc, -1, v27, vcc
	v_add_co_u32_e32 v164, vcc, 0xffff7000, v26
	global_load_dword v162, v[162:163], off
	s_nop 0
	global_load_dword v163, v[38:39], off
	v_addc_co_u32_e32 v165, vcc, -1, v27, vcc
	v_add_co_u32_e32 v38, vcc, 0xffff8000, v26
	s_add_u32 s38, s38, 64
	s_nop 0
	v_addc_co_u32_e32 v39, vcc, -1, v27, vcc
	v_add_co_u32_e32 v166, vcc, 0xffff9000, v26
	global_load_dword v164, v[164:165], off
	s_nop 0
	global_load_dword v165, v[38:39], off
	v_addc_co_u32_e32 v167, vcc, -1, v27, vcc
	v_add_co_u32_e32 v38, vcc, 0xffffa000, v26
	s_addc_u32 s39, s39, 0
	s_nop 0
	v_addc_co_u32_e32 v39, vcc, -1, v27, vcc
	v_add_co_u32_e32 v168, vcc, 0xffffb000, v26
	global_load_dword v166, v[166:167], off
	s_nop 0
	global_load_dword v167, v[38:39], off
	v_addc_co_u32_e32 v169, vcc, -1, v27, vcc
	v_add_co_u32_e32 v38, vcc, 0xffffc000, v26
	s_cmpk_lt_u32 s20, 0x70
	s_nop 0
	v_addc_co_u32_e32 v39, vcc, -1, v27, vcc
	v_add_co_u32_e32 v170, vcc, 0xffffd000, v26
	global_load_dword v168, v[168:169], off
	s_nop 0
	global_load_dword v169, v[38:39], off
	v_addc_co_u32_e32 v171, vcc, -1, v27, vcc
	v_add_co_u32_e32 v38, vcc, 0xffffe000, v26
	s_waitcnt vmcnt(14)
	v_pk_mul_f32 v[2:3], v[36:37], v[2:3]
	v_addc_co_u32_e32 v39, vcc, -1, v27, vcc
	global_load_dword v170, v[170:171], off
	s_nop 0
	global_load_dword v171, v[38:39], off
	s_waitcnt vmcnt(14)
	v_mul_f32_e32 v12, v24, v12
	s_waitcnt vmcnt(12)
	v_mul_f32_e32 v24, v172, v13
	s_waitcnt vmcnt(11)
	v_mul_f32_e32 v14, v173, v14
	s_waitcnt vmcnt(11) lgkmcnt(0)
	v_mov_b32_e32 v36, v54
	s_waitcnt vmcnt(11) lgkmcnt(0)
	v_mov_b32_e32 v37, v66
	v_mov_b32_e32 v38, v56
	v_mov_b32_e32 v39, v68
	v_mov_b32_e32 v68, v57
	s_waitcnt vmcnt(11) lgkmcnt(0)
	v_mov_b32_e32 v56, v82
	s_waitcnt vmcnt(11) lgkmcnt(0)
	v_mov_b32_e32 v57, v94
	s_waitcnt vmcnt(11) lgkmcnt(12)
	v_mov_b32_e32 v172, v110
	s_waitcnt vmcnt(11) lgkmcnt(8)
	v_mov_b32_e32 v173, v126
	v_mov_b32_e32 v66, v55
	v_mov_b32_e32 v94, v83
	v_mov_b32_e32 v126, v111
	s_waitcnt vmcnt(11) lgkmcnt(4)
	v_mov_b32_e32 v174, v142
	s_waitcnt vmcnt(11) lgkmcnt(0)
	v_mov_b32_e32 v175, v158
	v_pk_fma_f32 v[34:35], v[12:13], v[36:37], v[34:35] op_sel_hi:[0,1,1]
	v_pk_fma_f32 v[32:33], v[12:13], v[56:57], v[32:33] op_sel_hi:[0,1,1]
	v_pk_fma_f32 v[30:31], v[12:13], v[172:173], v[30:31] op_sel_hi:[0,1,1]
	v_mov_b32_e32 v82, v84
	v_mov_b32_e32 v83, v96
	v_mov_b32_e32 v110, v112
	v_mov_b32_e32 v111, v128
	v_mov_b32_e32 v158, v143
	v_pk_fma_f32 v[12:13], v[12:13], v[174:175], v[28:29] op_sel_hi:[0,1,1]
	v_pk_fma_f32 v[28:29], v[24:25], v[66:67], v[34:35] op_sel_hi:[0,1,1]
	v_pk_fma_f32 v[32:33], v[24:25], v[94:95], v[32:33] op_sel_hi:[0,1,1]
	v_pk_fma_f32 v[30:31], v[24:25], v[126:127], v[30:31] op_sel_hi:[0,1,1]
	v_mov_b32_e32 v54, v50
	v_mov_b32_e32 v96, v85
	v_mov_b32_e32 v128, v113
	v_mov_b32_e32 v142, v144
	v_mov_b32_e32 v143, v160
	v_mul_f32_e32 v50, v2, v132
	s_waitcnt vmcnt(10) lgkmcnt(0)
	v_mul_f32_e32 v132, v176, v15
	v_pk_fma_f32 v[12:13], v[24:25], v[158:159], v[12:13] op_sel_hi:[0,1,1]
	s_waitcnt vmcnt(8) lgkmcnt(0)
; __device__ __forceinline__ v4u pack8(const float (&f)[8]) { v4u w; w.x = pk2(f[0], f[1]); w.y = pk2(f[2], f[3]); w.z = pk2(f[4], f[5]); w.w = pk2(f[6], f[7]); return w; }
; template <int PART>
; __device__ __forceinline__ void phase_prologue_late(const Params& p, LAS unsigned char* lds, int cu0) {
;     ...
;                 for (int dd = 0; dd < 16; ++dd) { const float w = wv[dd] * sc[g * 128 + d0 + dd];
; #pragma unroll
;                     for (int i = 0; i < 8; ++i) acc[i] += wp[i * 128 + d0 + dd] * w; }
;             }
;             *(v4u*)(WT + (size_t)n * D + g * 128 + cb * 8) = pack8(acc);
;         }
	v_pk_mul_f32 v[8:9], v[162:163], v[8:9]
	v_pk_fma_f32 v[28:29], v[14:15], v[38:39], v[28:29] op_sel_hi:[0,1,1]
	v_pk_fma_f32 v[32:33], v[14:15], v[82:83], v[32:33] op_sel_hi:[0,1,1]
	v_pk_fma_f32 v[30:31], v[14:15], v[110:111], v[30:31] op_sel_hi:[0,1,1]
	v_mov_b32_e32 v55, v62
	v_mov_b32_e32 v84, v78
	v_mov_b32_e32 v85, v90
	v_mov_b32_e32 v112, v106
	v_mov_b32_e32 v113, v122
	v_mov_b32_e32 v160, v145
	v_pk_fma_f32 v[12:13], v[14:15], v[142:143], v[12:13] op_sel_hi:[0,1,1]
	v_pk_fma_f32 v[14:15], v[132:133], v[68:69], v[28:29] op_sel_hi:[0,1,1]
	v_pk_fma_f32 v[28:29], v[132:133], v[96:97], v[32:33] op_sel_hi:[0,1,1]
	v_pk_fma_f32 v[30:31], v[132:133], v[128:129], v[30:31] op_sel_hi:[0,1,1]
	v_pk_mul_f32 v[34:35], v[8:9], v[154:155]
	v_mov_b32_e32 v62, v51
	v_mov_b32_e32 v90, v79
	v_mov_b32_e32 v122, v107
	v_mul_f32_e32 v32, v8, v138
	v_pk_fma_f32 v[12:13], v[132:133], v[160:161], v[12:13] op_sel_hi:[0,1,1]
	v_pk_fma_f32 v[14:15], v[8:9], v[54:55], v[14:15] op_sel_hi:[0,1,1]
	v_pk_fma_f32 v[28:29], v[8:9], v[84:85], v[28:29] op_sel_hi:[0,1,1]
	v_pk_fma_f32 v[30:31], v[8:9], v[112:113], v[30:31] op_sel_hi:[0,1,1]
	v_mov_b32_e32 v33, v34
	s_waitcnt vmcnt(6) lgkmcnt(0)
	v_pk_mul_f32 v[10:11], v[164:165], v[10:11]
	v_mov_b32_e32 v106, v52
	v_mov_b32_e32 v107, v64
	v_mov_b32_e32 v64, v53
	v_mov_b32_e32 v52, v46
	v_mov_b32_e32 v53, v58
	v_mov_b32_e32 v58, v47
	v_mov_b32_e32 v46, v48
	v_mov_b32_e32 v47, v60
	v_mov_b32_e32 v60, v49
	v_mov_b32_e32 v48, v42
	v_mov_b32_e32 v49, v16
	v_mov_b32_e32 v16, v43
	v_mov_b32_e32 v42, v44
	v_mov_b32_e32 v43, v18
	v_mov_b32_e32 v18, v45
	v_mov_b32_e32 v44, v80
	v_mov_b32_e32 v45, v92
	v_mov_b32_e32 v92, v81
	v_mov_b32_e32 v80, v74
	v_mov_b32_e32 v81, v86
	v_mov_b32_e32 v86, v75
	v_mov_b32_e32 v74, v76
	v_mov_b32_e32 v75, v88
	v_mov_b32_e32 v88, v77
	v_mov_b32_e32 v76, v70
	v_mov_b32_e32 v77, v20
	v_mov_b32_e32 v20, v71
	v_mov_b32_e32 v70, v72
	v_mov_b32_e32 v71, v22
	v_mov_b32_e32 v22, v73
	v_mov_b32_e32 v72, v108
	v_mov_b32_e32 v73, v124
	v_mul_f32_e32 v34, v9, v139
	v_pk_add_f32 v[12:13], v[12:13], v[32:33]
	v_pk_mul_f32 v[36:37], v[10:11], v[156:157]
	v_pk_fma_f32 v[14:15], v[8:9], v[62:63], v[14:15] op_sel:[1,0,0]
	v_pk_fma_f32 v[28:29], v[8:9], v[90:91], v[28:29] op_sel:[1,0,0]
	v_pk_fma_f32 v[8:9], v[8:9], v[122:123], v[30:31] op_sel:[1,0,0]
	v_mov_b32_e32 v124, v109
	v_mul_f32_e32 v32, v10, v140
	s_waitcnt vmcnt(4) lgkmcnt(0)
	v_pk_mul_f32 v[4:5], v[166:167], v[4:5]
	v_pk_fma_f32 v[14:15], v[10:11], v[106:107], v[14:15] op_sel_hi:[0,1,1]
	v_pk_fma_f32 v[28:29], v[10:11], v[44:45], v[28:29] op_sel_hi:[0,1,1]
	v_pk_fma_f32 v[8:9], v[10:11], v[72:73], v[8:9] op_sel_hi:[0,1,1]
	v_pk_add_f32 v[12:13], v[12:13], v[34:35]
	v_mov_b32_e32 v33, v36
	v_mov_b32_e32 v108, v102
	v_mov_b32_e32 v109, v118
	v_mul_f32_e32 v38, v11, v141
	v_mov_b32_e32 v39, v37
	v_pk_mul_f32 v[34:35], v[4:5], v[150:151]
	v_pk_fma_f32 v[14:15], v[10:11], v[64:65], v[14:15] op_sel:[1,0,0]
	v_pk_fma_f32 v[28:29], v[10:11], v[92:93], v[28:29] op_sel:[1,0,0]
	v_pk_fma_f32 v[8:9], v[10:11], v[124:125], v[8:9] op_sel:[1,0,0]
	v_pk_add_f32 v[10:11], v[12:13], v[32:33]
	v_mov_b32_e32 v118, v103
	v_mul_f32_e32 v30, v4, v134
	s_waitcnt vmcnt(2) lgkmcnt(0)
	v_pk_mul_f32 v[6:7], v[168:169], v[6:7]
	v_pk_fma_f32 v[12:13], v[4:5], v[52:53], v[14:15] op_sel_hi:[0,1,1]
	v_pk_fma_f32 v[14:15], v[4:5], v[80:81], v[28:29] op_sel_hi:[0,1,1]
	v_pk_fma_f32 v[8:9], v[4:5], v[108:109], v[8:9] op_sel_hi:[0,1,1]
	v_pk_add_f32 v[10:11], v[10:11], v[38:39]
	v_mov_b32_e32 v31, v34
	v_mov_b32_e32 v102, v104
	v_mov_b32_e32 v103, v120
	v_mul_f32_e32 v36, v5, v135
	v_mov_b32_e32 v37, v35
	v_pk_mul_f32 v[32:33], v[6:7], v[152:153]
	v_pk_fma_f32 v[12:13], v[4:5], v[58:59], v[12:13] op_sel:[1,0,0]
	v_pk_fma_f32 v[14:15], v[4:5], v[86:87], v[14:15] op_sel:[1,0,0]
	v_pk_fma_f32 v[4:5], v[4:5], v[118:119], v[8:9] op_sel:[1,0,0]
	v_pk_add_f32 v[8:9], v[10:11], v[30:31]
	v_mov_b32_e32 v120, v105
	v_mul_f32_e32 v28, v6, v136
	s_waitcnt vmcnt(0) lgkmcnt(0)
	v_pk_mul_f32 v[0:1], v[170:171], v[0:1]
	v_pk_fma_f32 v[10:11], v[6:7], v[46:47], v[12:13] op_sel_hi:[0,1,1]
	v_pk_fma_f32 v[12:13], v[6:7], v[74:75], v[14:15] op_sel_hi:[0,1,1]
	v_pk_fma_f32 v[4:5], v[6:7], v[102:103], v[4:5] op_sel_hi:[0,1,1]
	v_pk_add_f32 v[8:9], v[8:9], v[36:37]
	v_mov_b32_e32 v29, v32
	v_mov_b32_e32 v104, v98
	v_mov_b32_e32 v105, v114
	v_mul_f32_e32 v34, v7, v137
	v_mov_b32_e32 v35, v33
	v_pk_mul_f32 v[30:31], v[0:1], v[146:147]
	v_pk_fma_f32 v[10:11], v[6:7], v[60:61], v[10:11] op_sel:[1,0,0]
	v_pk_fma_f32 v[12:13], v[6:7], v[88:89], v[12:13] op_sel:[1,0,0]
	v_pk_fma_f32 v[4:5], v[6:7], v[120:121], v[4:5] op_sel:[1,0,0]
	v_pk_add_f32 v[6:7], v[8:9], v[28:29]
	v_mov_b32_e32 v114, v99
	v_mul_f32_e32 v14, v0, v130
	v_pk_fma_f32 v[8:9], v[0:1], v[48:49], v[10:11] op_sel_hi:[0,1,1]
	v_pk_fma_f32 v[10:11], v[0:1], v[76:77], v[12:13] op_sel_hi:[0,1,1]
	v_pk_fma_f32 v[4:5], v[0:1], v[104:105], v[4:5] op_sel_hi:[0,1,1]
	v_pk_add_f32 v[6:7], v[6:7], v[34:35]
	v_mov_b32_e32 v15, v30
	v_pk_mul_f32 v[78:79], v[2:3], v[148:149]
	v_mov_b32_e32 v98, v100
	v_mov_b32_e32 v99, v116
	v_mul_f32_e32 v32, v1, v131
	v_mov_b32_e32 v33, v31
	v_pk_fma_f32 v[8:9], v[0:1], v[16:17], v[8:9] op_sel:[1,0,0]
	v_pk_fma_f32 v[10:11], v[0:1], v[20:21], v[10:11] op_sel:[1,0,0]
	v_pk_fma_f32 v[0:1], v[0:1], v[114:115], v[4:5] op_sel:[1,0,0]
	v_pk_add_f32 v[4:5], v[6:7], v[14:15]
	v_mov_b32_e32 v116, v101
	v_mov_b32_e32 v51, v78
	v_pk_fma_f32 v[0:1], v[2:3], v[98:99], v[0:1] op_sel_hi:[0,1,1]
	v_pk_add_f32 v[4:5], v[4:5], v[32:33]
	v_mul_f32_e32 v100, v3, v133
	v_mov_b32_e32 v101, v79
	v_pk_fma_f32 v[6:7], v[2:3], v[42:43], v[8:9] op_sel_hi:[0,1,1]
	v_pk_fma_f32 v[8:9], v[2:3], v[70:71], v[10:11] op_sel_hi:[0,1,1]
	v_pk_fma_f32 v[30:31], v[2:3], v[116:117], v[0:1] op_sel:[1,0,0]
	v_pk_add_f32 v[0:1], v[4:5], v[50:51]
	v_lshl_add_u64 v[26:27], v[26:27], 0, s[2:3]
	v_pk_fma_f32 v[34:35], v[2:3], v[18:19], v[6:7] op_sel:[1,0,0]
	v_pk_fma_f32 v[32:33], v[2:3], v[22:23], v[8:9] op_sel:[1,0,0]
	v_pk_add_f32 v[28:29], v[0:1], v[100:101]
	s_cbranch_scc1 .LBB0_511
	s_lshl_b32 s4, s9, 6
	s_and_b32 s4, s4, 0x3c0
	v_or_b32_e32 v4, s4, v41
	v_lshlrev_b32_e32 v24, 11, v4
	v_lshl_add_u64 v[4:5], s[0:1], 0, v[24:25]
	v_lshl_add_u64 v[4:5], s[22:23], 1, v[4:5]
	s_and_b32 s4, s9, 0xf0
	s_add_i32 s9, s9, s12
	s_add_i32 s15, s15, s16
	v_lshl_add_u64 v[4:5], v[4:5], 0, s[4:5]
	s_cmpk_gt_i32 s9, 0x3ff
	v_cvt_pk_bf16_f32 v0, v34, v35
	v_cvt_pk_bf16_f32 v1, v32, v33
	v_cvt_pk_bf16_f32 v2, v30, v31
	v_cvt_pk_bf16_f32 v3, v28, v29
	global_store_dwordx4 v[4:5], v[0:3], off sc1
	s_cbranch_scc0 .LBB0_510
